# grid barrier: first arriver of each XCD starts an un-waited L2 write-back (pre-drain before the leader's release write-back)
# baseline (speedup 1.0000x reference)
.LBB0_60:
	s_or_b64 exec, exec, s[8:9]
	v_cvt_f32_u32_e32 v4, v2
	s_waitcnt vmcnt(0)
	buffer_inv sc1
	v_readfirstlane_b32 s3, v3
	v_sub_u32_e32 v3, 0, v2
	v_rcp_iflag_f32_e32 v4, v4
	v_add_u32_e32 v5, s3, v1
	v_mul_f32_e32 v4, 0x4f7ffffe, v4
	v_cvt_u32_f32_e32 v4, v4
	v_mul_lo_u32 v1, v3, v4
	v_mul_hi_u32 v1, v4, v1
	v_add_u32_e32 v1, v4, v1
	v_mul_hi_u32 v1, v5, v1
	v_mul_lo_u32 v3, v1, v2
	v_sub_u32_e32 v3, v5, v3
	v_add_u32_e32 v4, 1, v1
	v_cmp_ge_u32_e32 vcc, v3, v2
	s_nop 1
	v_cndmask_b32_e32 v1, v1, v4, vcc
	v_sub_u32_e32 v4, v3, v2
	v_cndmask_b32_e32 v3, v3, v4, vcc
	v_add_u32_e32 v4, 1, v1
	v_cmp_ge_u32_e32 vcc, v3, v2
	v_add_u32_e32 v3, 1, v5
	s_nop 0
	v_cndmask_b32_e32 v1, v1, v4, vcc
	v_mul_lo_u32 v4, v2, v1
	v_add_u32_e32 v2, v4, v2
	v_cmp_ne_u32_e32 vcc, v3, v2
	s_and_saveexec_b64 s[6:7], vcc
	s_xor_b64 s[6:7], exec, s[6:7]
	s_cbranch_execz .LBB0_74
	s_waitcnt lgkmcnt(0)
	v_add_u32_e32 v4, 1, v4
	v_cmp_eq_u32_e32 vcc, v3, v4
	s_cbranch_vccz .Lbwb_skip0
	buffer_wbl2 sc1
.Lbwb_skip0:
	v_add_u32_e32 v1, 1, v1
	v_mul_lo_u32 v1, v1, v0
	s_add_u32 s12, s24, 0xed25400
	s_addc_u32 s13, s25, 0
	v_mov_b32_e32 v0, 0
	global_load_dword v0, v0, s[12:13] sc1
	s_waitcnt vmcnt(0)
	v_cmp_lt_u32_e32 vcc, v0, v1
	s_and_saveexec_b64 s[8:9], vcc
	s_cbranch_execz .LBB0_73
	s_add_u32 s10, s24, 0xed22200
	s_addc_u32 s11, s25, 0
	s_mov_b32 s3, 1
	s_mov_b64 s[14:15], 0
	v_mov_b32_e32 v0, 0
	s_branch .LBB0_64

.LBB0_954:
	s_or_b64 exec, exec, s[12:13]
	v_cvt_f32_u32_e32 v4, v2
	s_waitcnt vmcnt(0)
	buffer_inv sc1
	v_readfirstlane_b32 s3, v3
	v_sub_u32_e32 v3, 0, v2
	v_rcp_iflag_f32_e32 v4, v4
	v_add_u32_e32 v5, s3, v1
	v_mul_f32_e32 v4, 0x4f7ffffe, v4
	v_cvt_u32_f32_e32 v4, v4
	v_mul_lo_u32 v1, v3, v4
	v_mul_hi_u32 v1, v4, v1
	v_add_u32_e32 v1, v4, v1
	v_mul_hi_u32 v1, v5, v1
	v_mul_lo_u32 v3, v1, v2
	v_sub_u32_e32 v3, v5, v3
	v_add_u32_e32 v4, 1, v1
	v_cmp_ge_u32_e32 vcc, v3, v2
	s_nop 1
	v_cndmask_b32_e32 v1, v1, v4, vcc
	v_sub_u32_e32 v4, v3, v2
	v_cndmask_b32_e32 v3, v3, v4, vcc
	v_add_u32_e32 v4, 1, v1
	v_cmp_ge_u32_e32 vcc, v3, v2
	v_add_u32_e32 v3, 1, v5
	s_nop 0
	v_cndmask_b32_e32 v1, v1, v4, vcc
	v_mul_lo_u32 v4, v2, v1
	v_add_u32_e32 v2, v4, v2
	v_cmp_ne_u32_e32 vcc, v3, v2
	s_and_saveexec_b64 s[10:11], vcc
	s_xor_b64 s[10:11], exec, s[10:11]
	s_cbranch_execz .LBB0_968
	s_waitcnt lgkmcnt(0)
	v_add_u32_e32 v4, 1, v4
	v_cmp_eq_u32_e32 vcc, v3, v4
	s_cbranch_vccz .Lbwb_skip3
	buffer_wbl2 sc1
.Lbwb_skip3:
	v_add_u32_e32 v1, 1, v1
	v_mul_lo_u32 v1, v1, v0
	s_add_u32 s42, s24, 0xed25400
	s_addc_u32 s43, s25, 0
	v_mov_b32_e32 v0, 0
	global_load_dword v0, v0, s[42:43] sc1
	s_waitcnt vmcnt(0)
	v_cmp_lt_u32_e32 vcc, v0, v1
	s_and_saveexec_b64 s[12:13], vcc
	s_cbranch_execz .LBB0_967
	s_add_u32 s40, s24, 0xed22200
	s_addc_u32 s41, s25, 0
	s_mov_b32 s3, 1
	s_mov_b64 s[46:47], 0
	v_mov_b32_e32 v0, 0
	s_branch .LBB0_958

.LBB0_1090:
	s_or_b64 exec, exec, s[16:17]
	v_cvt_f32_u32_e32 v4, v2
	s_waitcnt vmcnt(0)
	buffer_inv sc1
	v_readfirstlane_b32 s3, v3
	v_sub_u32_e32 v3, 0, v2
	v_rcp_iflag_f32_e32 v4, v4
	v_add_u32_e32 v5, s3, v1
	v_mul_f32_e32 v4, 0x4f7ffffe, v4
	v_cvt_u32_f32_e32 v4, v4
	v_mul_lo_u32 v1, v3, v4
	v_mul_hi_u32 v1, v4, v1
	v_add_u32_e32 v1, v4, v1
	v_mul_hi_u32 v1, v5, v1
	v_mul_lo_u32 v3, v1, v2
	v_sub_u32_e32 v3, v5, v3
	v_add_u32_e32 v4, 1, v1
	v_cmp_ge_u32_e32 vcc, v3, v2
	s_nop 1
	v_cndmask_b32_e32 v1, v1, v4, vcc
	v_sub_u32_e32 v4, v3, v2
	v_cndmask_b32_e32 v3, v3, v4, vcc
	v_add_u32_e32 v4, 1, v1
	v_cmp_ge_u32_e32 vcc, v3, v2
	v_add_u32_e32 v3, 1, v5
	s_nop 0
	v_cndmask_b32_e32 v1, v1, v4, vcc
	v_mul_lo_u32 v4, v2, v1
	v_add_u32_e32 v2, v4, v2
	v_cmp_ne_u32_e32 vcc, v3, v2
	s_and_saveexec_b64 s[6:7], vcc
	s_xor_b64 s[6:7], exec, s[6:7]
	s_cbranch_execz .LBB0_1104
	s_waitcnt lgkmcnt(0)
	v_add_u32_e32 v4, 1, v4
	v_cmp_eq_u32_e32 vcc, v3, v4
	s_cbranch_vccz .Lbwb_skip5
	buffer_wbl2 sc1
.Lbwb_skip5:
	v_add_u32_e32 v1, 1, v1
	v_mul_lo_u32 v1, v1, v0
	s_add_u32 s46, s24, 0xed25400
	s_addc_u32 s47, s25, 0
	v_mov_b32_e32 v0, 0
	global_load_dword v0, v0, s[46:47] sc1
	s_waitcnt vmcnt(0)
	v_cmp_lt_u32_e32 vcc, v0, v1
	s_and_saveexec_b64 s[40:41], vcc
	s_cbranch_execz .LBB0_1103
	s_add_u32 s42, s24, 0xed22200
	s_addc_u32 s43, s25, 0
	s_mov_b32 s3, 1
	s_mov_b64 s[48:49], 0
	v_mov_b32_e32 v0, 0
	s_branch .LBB0_1094

.Lbwb_skip6:
	v_add_u32_e32 v1, 1, v1
	v_mul_lo_u32 v1, v1, v0
	s_add_u32 s40, s24, 0xed25400
	s_addc_u32 s41, s25, 0
	v_mov_b32_e32 v0, 0
	global_load_dword v0, v0, s[40:41] sc1
	s_waitcnt vmcnt(0)
	v_cmp_lt_u32_e32 vcc, v0, v1
	s_and_saveexec_b64 s[36:37], vcc
	s_cbranch_execz .LBB0_1233
	s_add_u32 s38, s24, 0xed22200
	s_addc_u32 s39, s25, 0
	s_mov_b32 s3, 1
	s_mov_b64 s[42:43], 0
	v_mov_b32_e32 v0, 0
	s_branch .LBB0_1224

.LBB0_1318:
	s_or_b64 exec, exec, s[14:15]
	v_cvt_f32_u32_e32 v4, v2
	s_waitcnt vmcnt(0)
	buffer_inv sc1
	v_readfirstlane_b32 s3, v3
	v_sub_u32_e32 v3, 0, v2
	v_rcp_iflag_f32_e32 v4, v4
	v_add_u32_e32 v5, s3, v1
	v_mul_f32_e32 v4, 0x4f7ffffe, v4
	v_cvt_u32_f32_e32 v4, v4
	v_mul_lo_u32 v1, v3, v4
	v_mul_hi_u32 v1, v4, v1
	v_add_u32_e32 v1, v4, v1
	v_mul_hi_u32 v1, v5, v1
	v_mul_lo_u32 v3, v1, v2
	v_sub_u32_e32 v3, v5, v3
	v_add_u32_e32 v4, 1, v1
	v_cmp_ge_u32_e32 vcc, v3, v2
	s_nop 1
	v_cndmask_b32_e32 v1, v1, v4, vcc
	v_sub_u32_e32 v4, v3, v2
	v_cndmask_b32_e32 v3, v3, v4, vcc
	v_add_u32_e32 v4, 1, v1
	v_cmp_ge_u32_e32 vcc, v3, v2
	v_add_u32_e32 v3, 1, v5
	s_nop 0
	v_cndmask_b32_e32 v1, v1, v4, vcc
	v_mul_lo_u32 v4, v2, v1
	v_add_u32_e32 v2, v4, v2
	v_cmp_ne_u32_e32 vcc, v3, v2
	s_and_saveexec_b64 s[6:7], vcc
	s_xor_b64 s[6:7], exec, s[6:7]
	s_cbranch_execz .LBB0_1332
	s_waitcnt lgkmcnt(0)
	v_add_u32_e32 v4, 1, v4
	v_cmp_eq_u32_e32 vcc, v3, v4
	s_cbranch_vccz .Lbwb_skip7
	buffer_wbl2 sc1
.Lbwb_skip7:
	v_add_u32_e32 v1, 1, v1
	v_mul_lo_u32 v1, v1, v0
	s_add_u32 s38, s24, 0xed25400
	s_addc_u32 s39, s25, 0
	v_mov_b32_e32 v0, 0
	global_load_dword v0, v0, s[38:39] sc1
	s_waitcnt vmcnt(0)
	v_cmp_lt_u32_e32 vcc, v0, v1
	s_and_saveexec_b64 s[14:15], vcc
	s_cbranch_execz .LBB0_1331
	s_add_u32 s36, s24, 0xed22200
	s_addc_u32 s37, s25, 0
	s_mov_b32 s3, 1
	s_mov_b64 s[40:41], 0
	v_mov_b32_e32 v0, 0
	s_branch .LBB0_1322

.LBB0_1522:
	s_or_b64 exec, exec, s[8:9]
	v_cvt_f32_u32_e32 v4, v2
	s_waitcnt vmcnt(0)
	buffer_inv sc1
	v_readfirstlane_b32 s6, v3
	v_sub_u32_e32 v3, 0, v2
	v_rcp_iflag_f32_e32 v4, v4
	v_add_u32_e32 v5, s6, v1
	v_mul_f32_e32 v4, 0x4f7ffffe, v4
	v_cvt_u32_f32_e32 v4, v4
	v_mul_lo_u32 v1, v3, v4
	v_mul_hi_u32 v1, v4, v1
	v_add_u32_e32 v1, v4, v1
	v_mul_hi_u32 v1, v5, v1
	v_mul_lo_u32 v3, v1, v2
	v_sub_u32_e32 v3, v5, v3
	v_add_u32_e32 v4, 1, v1
	v_cmp_ge_u32_e32 vcc, v3, v2
	s_nop 1
	v_cndmask_b32_e32 v1, v1, v4, vcc
	v_sub_u32_e32 v4, v3, v2
	v_cndmask_b32_e32 v3, v3, v4, vcc
	v_add_u32_e32 v4, 1, v1
	v_cmp_ge_u32_e32 vcc, v3, v2
	v_add_u32_e32 v3, 1, v5
	s_nop 0
	v_cndmask_b32_e32 v1, v1, v4, vcc
	v_mul_lo_u32 v4, v2, v1
	v_add_u32_e32 v2, v4, v2
	v_cmp_ne_u32_e32 vcc, v3, v2
	s_and_saveexec_b64 s[6:7], vcc
	s_xor_b64 s[6:7], exec, s[6:7]
	s_cbranch_execz .LBB0_1536
	s_waitcnt lgkmcnt(0)
	v_add_u32_e32 v4, 1, v4
	v_cmp_eq_u32_e32 vcc, v3, v4
	s_cbranch_vccz .Lbwb_skip10
	buffer_wbl2 sc1
.Lbwb_skip10:
	v_add_u32_e32 v1, 1, v1
	v_mul_lo_u32 v1, v1, v0
	s_add_u32 s14, s24, 0xed25400
	s_addc_u32 s15, s25, 0
	v_mov_b32_e32 v0, 0
	global_load_dword v0, v0, s[14:15] sc1
	s_waitcnt vmcnt(0)
	v_cmp_lt_u32_e32 vcc, v0, v1
	s_and_saveexec_b64 s[8:9], vcc
	s_cbranch_execz .LBB0_1535
	s_add_u32 s12, s24, 0xed22200
	s_addc_u32 s13, s25, 0
	s_mov_b32 s19, 1
	s_mov_b64 s[16:17], 0
	v_mov_b32_e32 v0, 0
	s_branch .LBB0_1526
